# GEMM prologues (6 sites): K-tile 1's six LDS-DMA loads issued together with K-tile 0's eight (wait moved behind them as vmcnt(8)); P5 staging count adjusted
# baseline (speedup 1.0000x reference)
.LBB0_84:
	v_bfe_u32 v1, v20, 4, 2
	v_and_b32_e32 v182, 15, v20
	v_lshlrev_b32_e32 v21, 4, v1
	v_lshlrev_b32_e32 v20, 2, v20
	s_and_b32 s16, s15, 3
	s_lshl_b32 s34, s14, 6
	v_lshl_or_b32 v21, v182, 6, v21
	s_lshl_b32 s14, s14, 13
	v_and_b32_e32 v20, 32, v20
	s_add_i32 m0, s28, 0x18000
	v_lshl_add_u64 v[10:11], v[10:11], 0, s[96:97]
	v_bitop3_b32 v22, v21, s14, v20 bitop3:0xde
	s_lshl_b32 s35, s16, 5
	s_lshl_b32 s14, s16, 12
	global_load_lds_dwordx4 v[10:11], off
	v_lshl_add_u64 v[8:9], v[8:9], 0, s[96:97]
	s_add_i32 m0, s28, 0x1a000
	s_add_i32 s36, s28, 0x8000
	s_add_i32 s37, s28, 0xa000
	v_bitop3_b32 v183, v21, s14, v20 bitop3:0xde
	global_load_lds_dwordx4 v[8:9], off
	v_lshl_add_u64 v[6:7], v[6:7], 0, s[96:97]
	s_mov_b32 m0, s36
	s_add_u32 s14, s20, 0xb0080
	global_load_lds_dwordx4 v[6:7], off
	v_lshl_add_u64 v[4:5], v[4:5], 0, s[96:97]
	s_mov_b32 m0, s37
	s_addc_u32 s15, s21, 0
	global_load_lds_dwordx4 v[4:5], off
	s_add_i32 m0, s28, 0x1c000
	v_lshl_add_u64 v[4:5], s[14:15], 0, v[2:3]
	global_load_lds_dwordx4 v[4:5], off
	v_lshl_add_u64 v[4:5], s[14:15], 0, v[156:157]
	s_add_i32 m0, s28, 0x1e000
	s_add_u32 s48, s6, 0x2680000
	global_load_lds_dwordx4 v[4:5], off
	s_addc_u32 s49, s7, 0
	s_lshl_b32 s14, s16, 2
	s_add_u32 s14, s6, s14
	s_addc_u32 s15, s7, 0
	s_movk_i32 s16, 0xb00
	s_add_u32 s50, s14, 0x100000
	v_lshrrev_b32_e32 v5, 1, v17
	v_mul_lo_u32 v4, v16, s16
	s_mov_b32 s17, 0xb000
	s_addc_u32 s51, s15, 0
	v_mad_u64_u32 v[4:5], s[14:15], v5, s17, v[4:5]
	v_or_b32_e32 v4, v4, v18
	v_add_lshl_u32 v4, v4, v19, 1
	v_mov_b32_e32 v5, v3
	s_mov_b64 s[22:23], 0xb0080
	v_lshl_add_u64 v[162:163], v[4:5], 0, s[22:23]
	v_lshrrev_b32_e32 v5, 1, v12
	v_mul_lo_u32 v4, v13, s16
	v_mad_u64_u32 v[4:5], s[14:15], v5, s17, v[4:5]
	s_waitcnt vmcnt(8)
	s_barrier
	s_waitcnt vmcnt(6)
	v_or_b32_e32 v4, v4, v14
	v_add_lshl_u32 v4, v4, v15, 1
	v_mov_b32_e32 v5, v3
	v_readlane_b32 s14, v254, 13
	v_lshl_add_u64 v[164:165], v[4:5], 0, s[22:23]
	s_mov_b32 s52, 0
	v_add_u32_e32 v184, 0, v22
	v_readlane_b32 s55, v254, 17
	s_mov_b32 s56, s14
	s_barrier
	v_readlane_b32 s15, v254, 14
	s_branch .LBB0_86

.LBB0_142:
	v_bfe_u32 v206, v19, 4, 2
	v_and_b32_e32 v1, 15, v19
	v_lshlrev_b32_e32 v20, 4, v206
	v_lshlrev_b32_e32 v19, 2, v19
	s_and_b32 s22, s20, 3
	v_lshl_or_b32 v20, v1, 6, v20
	s_lshl_b32 s20, s18, 13
	v_and_b32_e32 v19, 32, v19
	s_add_i32 m0, s25, 0x18000
	v_lshl_add_u64 v[10:11], v[10:11], 0, s[96:97]
	s_lshl_b32 s29, s18, 6
	v_bitop3_b32 v21, v20, s20, v19 bitop3:0xde
	s_lshl_b32 s30, s22, 5
	s_lshl_b32 s20, s22, 12
	global_load_lds_dwordx4 v[10:11], off
	v_lshl_add_u64 v[8:9], v[8:9], 0, s[96:97]
	s_add_i32 m0, s25, 0x1a000
	s_add_i32 s31, s25, 0x8000
	s_add_i32 s34, s25, 0xa000
	v_bitop3_b32 v207, v20, s20, v19 bitop3:0xde
	global_load_lds_dwordx4 v[8:9], off
	v_lshl_add_u64 v[4:5], v[4:5], 0, s[96:97]
	s_mov_b32 m0, s31
	s_add_u32 s20, s16, 0xb0080
	global_load_lds_dwordx4 v[4:5], off
	v_lshl_add_u64 v[4:5], v[6:7], 0, s[96:97]
	s_mov_b32 m0, s34
	s_addc_u32 s21, s17, 0
	global_load_lds_dwordx4 v[4:5], off
	s_add_i32 m0, s25, 0x1c000
	v_lshl_add_u64 v[4:5], s[20:21], 0, v[160:161]
	global_load_lds_dwordx4 v[4:5], off
	v_lshl_add_u64 v[4:5], s[20:21], 0, v[156:157]
	s_add_i32 m0, s25, 0x1e000
	s_cmpk_lt_u32 s19, 0x100
	global_load_lds_dwordx4 v[4:5], off
	s_cselect_b64 s[50:51], -1, 0
	s_lshl_b32 s19, s18, 2
	s_or_b32 s19, s19, s22
	s_lshl_b32 s36, s18, 8
	s_mul_i32 s37, s19, 0x900
	s_lshl_b32 s35, s19, 6
	s_add_i32 s36, s36, 0x20000
	s_add_i32 s37, s37, 0x20800
	s_add_u32 s52, s6, 0x2680000
	s_addc_u32 s53, s7, 0
	s_add_u32 s54, s6, 0x100000
	s_movk_i32 s20, 0xb00
	s_addc_u32 s55, s7, 0
	s_lshl_b32 s18, s22, 2
	v_lshrrev_b32_e32 v4, 1, v16
	v_mul_lo_u32 v2, v2, s20
	s_mov_b32 s21, 0xb000
	s_add_u32 s58, s54, s18
	v_mad_u64_u32 v[4:5], s[18:19], v4, s21, v[2:3]
	v_or_b32_e32 v2, v4, v17
	v_add_lshl_u32 v2, v2, v18, 1
	s_mov_b64 s[22:23], 0xb0080
	v_lshl_add_u64 v[164:165], v[2:3], 0, s[22:23]
	v_lshrrev_b32_e32 v4, 1, v12
	v_mul_lo_u32 v2, v13, s20
	v_mad_u64_u32 v[4:5], s[18:19], v4, s21, v[2:3]
	s_waitcnt vmcnt(8)
	s_barrier
	s_waitcnt vmcnt(6)
	s_addc_u32 s59, s55, 0
	v_or_b32_e32 v2, v4, v14
	s_add_u32 s60, s6, 0xe0000
	v_add_lshl_u32 v2, v2, v15, 1
	v_readlane_b32 s18, v254, 13
	s_addc_u32 s61, s7, 0
	v_lshl_add_u64 v[166:167], v[2:3], 0, s[22:23]
	s_mov_b32 s62, 0
	v_add_u32_e32 v208, 0, v21
	s_lshl_b32 s63, s30, 2
	v_readlane_b32 s23, v254, 17
	s_mov_b32 s22, s18
	s_barrier
	v_readlane_b32 s19, v254, 14
	s_branch .LBB0_145

.LBB0_306:
	s_waitcnt vmcnt(0)
	v_bfe_u32 v144, v18, 4, 2
	v_and_b32_e32 v1, 15, v18
	v_lshlrev_b32_e32 v19, 4, v144
	v_lshlrev_b32_e32 v18, 2, v18
	s_and_b32 s19, s16, 3
	v_lshl_or_b32 v19, v1, 6, v19
	s_lshl_b32 s16, s22, 13
	v_and_b32_e32 v18, 32, v18
	s_add_i32 m0, s45, 0x18000
	v_lshl_add_u64 v[10:11], v[10:11], 0, s[96:97]
	s_lshl_b32 s49, s22, 6
	v_bitop3_b32 v20, v19, s16, v18 bitop3:0xde
	s_lshl_b32 s50, s19, 5
	s_lshl_b32 s16, s19, 12
	global_load_lds_dwordx4 v[10:11], off
	v_lshl_add_u64 v[8:9], v[8:9], 0, s[96:97]
	s_add_i32 m0, s45, 0x1a000
	s_add_i32 s51, s45, 0x8000
	s_add_i32 s52, s45, 0xa000
	v_bitop3_b32 v145, v19, s16, v18 bitop3:0xde
	global_load_lds_dwordx4 v[8:9], off
	v_lshl_add_u64 v[4:5], v[4:5], 0, s[96:97]
	s_mov_b32 m0, s51
	s_add_u32 s16, s30, 0x40080
	global_load_lds_dwordx4 v[4:5], off
	v_lshl_add_u64 v[4:5], v[6:7], 0, s[96:97]
	s_mov_b32 m0, s52
	s_addc_u32 s17, s31, 0
	global_load_lds_dwordx4 v[4:5], off
	s_add_i32 m0, s45, 0x1c000
	v_lshl_add_u64 v[4:5], s[16:17], 0, v[2:3]
	global_load_lds_dwordx4 v[4:5], off
	v_lshl_add_u64 v[4:5], s[16:17], 0, v[132:133]
	s_add_i32 m0, s45, 0x1e000
	s_cmpk_lt_u32 s18, 0x100
	global_load_lds_dwordx4 v[4:5], off
	v_lshlrev_b32_e32 v4, 14, v16
	v_and_b32_e32 v4, 0xffff8000, v4
	s_cselect_b64 s[16:17], -1, 0
	s_and_b32 s18, s18, 0xffffff00
	s_lshl_b32 s19, s19, 6
	v_lshl_add_u32 v4, v15, 11, v4
	v_and_b32_e32 v5, 1, v16
	s_or_b32 s53, s19, s18
	v_lshl_or_b32 v4, v5, 6, v4
	s_add_u32 s18, s6, 0x380000
	v_lshl_add_u32 v138, v17, 1, v4
	v_lshlrev_b32_e32 v4, 14, v12
	s_addc_u32 s19, s7, 0
	v_and_b32_e32 v4, 0xffff8000, v4
	s_waitcnt vmcnt(8)
	s_barrier
	s_waitcnt vmcnt(6)
	s_add_u32 s20, s6, 0x4700000
	v_lshl_add_u32 v4, v13, 11, v4
	v_and_b32_e32 v5, 1, v12
	s_addc_u32 s21, s7, 0
	s_lshl_b32 s54, s22, 8
	v_lshl_or_b32 v4, v5, 6, v4
	v_readlane_b32 s22, v253, 60
	s_add_i32 s54, s54, 0x20000
	v_mov_b32_e32 v139, v3
	v_lshl_add_u32 v140, v14, 1, v4
	v_mov_b32_e32 v141, v3
	s_mov_b32 s55, 0
	v_add_u32_e32 v146, 0, v20
	v_readlane_b32 s56, v253, 57
	s_mov_b32 s57, s22
	s_barrier
	v_readlane_b32 s23, v253, 61
	s_branch .LBB0_309

.LBB0_331:
	v_bfe_u32 v1, v18, 4, 2
	v_and_b32_e32 v182, 15, v18
	v_lshlrev_b32_e32 v19, 4, v1
	v_lshlrev_b32_e32 v18, 2, v18
	s_and_b32 s16, s15, 3
	s_lshl_b32 s30, s14, 6
	v_lshl_or_b32 v19, v182, 6, v19
	s_lshl_b32 s14, s14, 13
	v_and_b32_e32 v18, 32, v18
	s_add_i32 m0, s26, 0x18000
	v_lshl_add_u64 v[10:11], v[10:11], 0, s[96:97]
	v_bitop3_b32 v20, v19, s14, v18 bitop3:0xde
	s_lshl_b32 s31, s16, 5
	s_lshl_b32 s14, s16, 12
	global_load_lds_dwordx4 v[10:11], off
	v_lshl_add_u64 v[8:9], v[8:9], 0, s[96:97]
	s_add_i32 m0, s26, 0x1a000
	s_add_i32 s34, s26, 0x8000
	s_add_i32 s35, s26, 0xa000
	v_bitop3_b32 v183, v19, s14, v18 bitop3:0xde
	global_load_lds_dwordx4 v[8:9], off
	v_lshl_add_u64 v[6:7], v[6:7], 0, s[96:97]
	s_mov_b32 m0, s34
	s_add_u32 s14, s20, 0x40080
	global_load_lds_dwordx4 v[6:7], off
	v_lshl_add_u64 v[4:5], v[4:5], 0, s[96:97]
	s_mov_b32 m0, s35
	s_addc_u32 s15, s21, 0
	global_load_lds_dwordx4 v[4:5], off
	s_add_i32 m0, s26, 0x1c000
	v_lshl_add_u64 v[4:5], s[14:15], 0, v[2:3]
	global_load_lds_dwordx4 v[4:5], off
	v_lshl_add_u64 v[4:5], s[14:15], 0, v[156:157]
	s_add_i32 m0, s26, 0x1e000
	s_add_u32 s48, s6, 0x2680000
	global_load_lds_dwordx4 v[4:5], off
	v_lshlrev_b32_e32 v4, 14, v16
	v_and_b32_e32 v4, 0xffff8000, v4
	v_lshl_add_u32 v4, v15, 11, v4
	v_and_b32_e32 v5, 1, v16
	s_addc_u32 s49, s7, 0
	s_lshl_b32 s14, s16, 2
	v_lshl_or_b32 v4, v5, 6, v4
	s_add_u32 s14, s6, s14
	v_lshl_add_u32 v162, v17, 1, v4
	v_lshlrev_b32_e32 v4, 14, v12
	s_addc_u32 s15, s7, 0
	v_and_b32_e32 v4, 0xffff8000, v4
	s_waitcnt vmcnt(8)
	s_barrier
	s_waitcnt vmcnt(6)
	s_add_u32 s36, s14, 0x380000
	v_lshl_add_u32 v4, v13, 11, v4
	v_and_b32_e32 v5, 1, v12
	s_addc_u32 s37, s15, 0
	v_lshl_or_b32 v4, v5, 6, v4
	v_readlane_b32 s14, v254, 13
	v_mov_b32_e32 v163, v3
	v_lshl_add_u32 v164, v14, 1, v4
	v_mov_b32_e32 v165, v3
	s_mov_b32 s54, 0
	v_add_u32_e32 v184, 0, v20
	v_readlane_b32 s55, v254, 17
	s_mov_b32 s42, s14
	s_barrier
	v_readlane_b32 s15, v254, 14
	s_branch .LBB0_333

.LBB0_381:
	v_bfe_u32 v235, v20, 4, 2
	v_and_b32_e32 v1, 15, v20
	v_lshlrev_b32_e32 v21, 4, v235
	v_lshlrev_b32_e32 v20, 2, v20
	s_and_b32 s38, s16, 3
	v_lshl_or_b32 v21, v1, 6, v21
	s_lshl_b32 s16, s14, 13
	v_and_b32_e32 v20, 32, v20
	s_add_i32 m0, s28, 0x18000
	v_lshl_add_u64 v[10:11], v[10:11], 0, s[96:97]
	s_lshl_b32 s34, s14, 6
	v_bitop3_b32 v22, v21, s16, v20 bitop3:0xde
	s_lshl_b32 s35, s38, 5
	s_lshl_b32 s16, s38, 12
	global_load_lds_dwordx4 v[10:11], off
	v_lshl_add_u64 v[8:9], v[8:9], 0, s[96:97]
	s_add_i32 m0, s28, 0x1a000
	s_add_i32 s36, s28, 0x8000
	s_add_i32 s37, s28, 0xa000
	v_bitop3_b32 v236, v21, s16, v20 bitop3:0xde
	global_load_lds_dwordx4 v[8:9], off
	v_lshl_add_u64 v[4:5], v[4:5], 0, s[96:97]
	s_mov_b32 m0, s36
	s_add_u32 s16, s18, 0x60080
	global_load_lds_dwordx4 v[4:5], off
	v_lshl_add_u64 v[4:5], v[6:7], 0, s[96:97]
	s_mov_b32 m0, s37
	s_addc_u32 s17, s19, 0
	global_load_lds_dwordx4 v[4:5], off
	s_add_i32 m0, s28, 0x1c000
	v_lshl_add_u64 v[4:5], s[16:17], 0, v[2:3]
	global_load_lds_dwordx4 v[4:5], off
	v_lshl_add_u64 v[4:5], s[16:17], 0, v[206:207]
	s_add_i32 m0, s28, 0x1e000
	s_add_u32 s44, s6, 0xb0a0000
	global_load_lds_dwordx4 v[4:5], off
	s_addc_u32 s45, s7, 0
	s_and_b32 s77, s15, 0xffffff00
	s_lshl_b32 s75, s14, 5
	s_lshl_b32 s76, s38, 3
	s_add_i32 s77, s77, 0x20000
	s_cmpk_lt_u32 s15, 0x100
	s_movk_i32 s17, 0x600
	s_cselect_b64 s[46:47], -1, 0
	s_add_u32 s48, s6, 0x7fe0000
	v_lshrrev_b32_e32 v5, 1, v17
	v_mul_lo_u32 v4, v16, s17
	s_movk_i32 s16, 0x6000
	s_addc_u32 s49, s7, 0
	s_lshl_b32 s78, s14, 8
	v_mad_u64_u32 v[4:5], s[14:15], v5, s16, v[4:5]
	v_or_b32_e32 v4, v4, v18
	v_add_lshl_u32 v212, v4, v19, 1
	v_lshrrev_b32_e32 v5, 1, v12
	v_mul_lo_u32 v4, v13, s17
	v_readlane_b32 s100, v254, 5
	v_readlane_b32 s101, v254, 6
	v_cmp_gt_i32_e32 vcc, 0x100, v234
	s_nop 1
	s_and_b64 s[100:101], s[100:101], vcc
	s_and_saveexec_b64 s[100:101], s[100:101]
	s_cbranch_execz .Lp5st_skip
	s_waitcnt vmcnt(14)
	v_mov_b32_e32 v176, v160
	v_mov_b32_e32 v177, v172
	v_mov_b32_e32 v172, v161
	v_pk_add_f32 v[160:161], v[176:177], v[172:173]
	v_mov_b32_e32 v172, v162
	v_mov_b32_e32 v173, v174
	v_mov_b32_e32 v174, v163
	v_pk_add_f32 v[162:163], v[172:173], v[174:175]
	s_nop 0
	v_pk_add_f32 v[160:161], v[160:161], v[162:163]
	v_mov_b32_e32 v162, v164
	v_mov_b32_e32 v163, v168
	v_mov_b32_e32 v168, v165
	v_mov_b32_e32 v164, v166
	v_mov_b32_e32 v165, v170
	v_mov_b32_e32 v170, v167
	v_pk_add_f32 v[162:163], v[162:163], v[168:169]
	v_pk_add_f32 v[164:165], v[164:165], v[170:171]
	s_nop 0
	v_pk_add_f32 v[162:163], v[162:163], v[164:165]
	s_nop 0
	v_pk_add_f32 v[160:161], v[160:161], v[162:163]
	s_nop 0
	v_add_f32_e32 v178, v160, v161
	v_fmamk_f32 v178, v178, 0x3a800000, v223
	v_cmp_gt_f32_e32 vcc, 0x800000, v178
	v_mul_f32_e32 v179, 0x4b800000, v178
	s_nop 0
	v_cndmask_b32_e32 v178, v178, v179, vcc
	v_rsq_f32_e32 v178, v178
	s_nop 0
	v_mul_f32_e32 v179, 0x45800000, v178
	v_cndmask_b32_e32 v178, v178, v179, vcc
	v_lshl_add_u32 v179, v234, 2, v225
	ds_write_b32 v179, v178
.Lp5st_skip:
	s_or_b64 exec, exec, s[100:101]
	s_waitcnt vmcnt(8)
	s_barrier
	s_waitcnt vmcnt(6)
	v_mad_u64_u32 v[4:5], s[14:15], v5, s16, v[4:5]
	v_or_b32_e32 v4, v4, v14
	v_readlane_b32 s14, v254, 13
	s_add_i32 s78, s78, 0x20000
	v_mov_b32_e32 v213, v3
	v_add_lshl_u32 v214, v4, v15, 1
	v_mov_b32_e32 v215, v3
	s_mov_b32 s79, 0
	v_add_u32_e32 v237, 0, v22
	v_readlane_b32 s82, v254, 17
	s_mov_b32 s16, s14
	s_barrier
	v_readlane_b32 s15, v254, 14
	s_branch .LBB0_384

.LBB0_742:
	s_lshl_b32 s26, s48, 4
	s_ashr_i32 s27, s26, 31
	s_lshl_b64 s[26:27], s[26:27], 2
	s_waitcnt vmcnt(0)
	v_bfe_u32 v156, v17, 4, 2
	s_waitcnt lgkmcnt(0)
	s_add_u32 s44, s22, s26
	v_and_b32_e32 v1, 15, v17
	v_lshlrev_b32_e32 v18, 4, v156
	v_lshlrev_b32_e32 v17, 2, v17
	s_addc_u32 s45, s23, s27
	s_and_b32 s15, s25, 3
	v_lshl_or_b32 v18, v1, 6, v18
	s_lshl_b32 s17, s34, 13
	v_and_b32_e32 v17, 32, v17
	s_add_i32 m0, s36, 0x18000
	v_lshl_add_u64 v[10:11], v[10:11], 0, s[96:97]
	s_lshl_b32 s66, s34, 6
	v_bitop3_b32 v19, v18, s17, v17 bitop3:0xde
	s_lshl_b32 s17, s15, 5
	s_lshl_b32 s22, s15, 12
	global_load_lds_dwordx4 v[10:11], off
	v_lshl_add_u64 v[8:9], v[8:9], 0, s[96:97]
	s_add_i32 m0, s36, 0x1a000
	s_add_i32 s67, s36, 0x8000
	s_add_i32 s68, s36, 0xa000
	v_bitop3_b32 v157, v18, s22, v17 bitop3:0xde
	global_load_lds_dwordx4 v[8:9], off
	v_lshl_add_u64 v[4:5], v[4:5], 0, s[96:97]
	s_mov_b32 m0, s67
	s_add_u32 s22, s20, 0x40080
	global_load_lds_dwordx4 v[4:5], off
	v_lshl_add_u64 v[4:5], v[6:7], 0, s[96:97]
	s_mov_b32 m0, s68
	s_addc_u32 s23, s21, 0
	global_load_lds_dwordx4 v[4:5], off
	s_add_i32 m0, s36, 0x1c000
	v_lshl_add_u64 v[4:5], s[22:23], 0, v[134:135]
	global_load_lds_dwordx4 v[4:5], off
	v_lshl_add_u64 v[4:5], s[22:23], 0, v[138:139]
	s_add_i32 m0, s36, 0x1e000
	s_cmpk_lt_u32 s24, 0x100
	global_load_lds_dwordx4 v[4:5], off
	s_mov_b32 s88, s48
	s_cselect_b64 s[46:47], -1, 0
	s_add_u32 s48, s6, 0x4c0000
	v_lshlrev_b32_e32 v4, 14, v2
	s_addc_u32 s49, s7, 0
	s_and_b32 s22, s24, 0xffffff00
	s_lshl_b32 s23, s15, 6
	v_and_b32_e32 v4, 0xffff8000, v4
	s_or_b32 s69, s23, s22
	v_lshl_add_u32 v4, v12, 11, v4
	v_and_b32_e32 v2, 1, v2
	s_add_u32 s50, s6, 0x100000
	v_lshl_or_b32 v2, v2, 6, v4
	s_addc_u32 s51, s7, 0
	s_lshl_b32 s70, s34, 8
	v_lshl_add_u32 v140, v13, 1, v2
	v_lshlrev_b32_e32 v2, 14, v14
	s_add_i32 s70, s70, 0x20000
	s_lshl_b32 s71, s15, 3
	v_and_b32_e32 v2, 0xffff8000, v2
	s_waitcnt vmcnt(8)
	s_barrier
	s_waitcnt vmcnt(6)
	s_cmp_eq_u32 s15, 0
	v_lshl_add_u32 v2, v15, 11, v2
	v_and_b32_e32 v4, 1, v14
	s_cselect_b64 s[52:53], -1, 0
	s_add_u32 s73, s6, 0xb0a0000
	v_lshl_or_b32 v2, v4, 6, v2
	s_mov_b32 s72, 0
	s_addc_u32 s74, s7, 0
	s_or_b32 s75, s71, 1
	s_or_b32 s76, s71, 2
	s_or_b32 s77, s71, 3
	s_or_b32 s78, s71, 4
	s_or_b32 s79, s71, 5
	s_or_b32 s80, s71, 6
	s_or_b32 s81, s71, 7
	v_mov_b32_e32 v141, v3
	v_lshl_add_u32 v142, v16, 1, v2
	v_mov_b32_e32 v143, v3
	v_add_u32_e32 v158, 0, v19
	s_lshl_b32 s82, s17, 1
	s_barrier
	s_mov_b32 s100, 0
	s_branch .LBB0_745
